# P6/P11 epilogue: IEEE 1/sqrt expansion (27 VALU) replaced by v_rsq_f32 + one Newton step (f32)
# speedup vs baseline: 1.0055x; 1.0055x over previous
.LBB0_779:
	v_lshl_add_u32 v148, s4, 8, v150
	v_ashrrev_i32_e32 v149, 31, v148
	v_lshlrev_b64 v[146:147], 6, v[148:149]
	v_lshl_add_u64 v[146:147], v[136:137], 0, v[146:147]
	s_mov_b64 s[98:99], 0x2000
	global_load_dwordx4 v[160:163], v[146:147], off
	global_load_dwordx4 v[206:209], v[146:147], off offset:1024
	global_load_dwordx4 v[210:213], v[146:147], off offset:2048
	global_load_dwordx4 v[214:217], v[146:147], off offset:3072
	v_lshl_add_u64 v[234:235], v[146:147], 0, s[98:99]
	global_load_dwordx4 v[218:221], v[234:235], off
	global_load_dwordx4 v[222:225], v[234:235], off offset:1024
	global_load_dwordx4 v[226:229], v[234:235], off offset:2048
	global_load_dwordx4 v[230:233], v[234:235], off offset:3072
	v_and_b32_e32 v159, 64, v156
	v_xor_b32_e32 v147, 16, v156
	v_add_u32_e32 v167, 64, v159
	v_cmp_lt_i32_e32 vcc, v147, v167
	v_xor_b32_e32 v166, 32, v156
	v_lshl_or_b32 v146, s5, 8, v152
	v_cndmask_b32_e32 v147, v156, v147, vcc
	v_lshlrev_b32_e32 v159, 2, v147
	v_cmp_lt_i32_e32 vcc, v166, v167
	v_ashrrev_i32_e32 v147, 31, v146
	v_lshlrev_b64 v[146:147], 1, v[146:147]
	s_waitcnt vmcnt(7)
	v_mov_b32_e32 v164, v161
	v_mov_b32_e32 v165, v162
	v_mov_b32_e32 v161, v163
	v_pk_add_f32 v[160:161], v[164:165], v[160:161]
	v_lshlrev_b64 v[164:165], 13, v[148:149]
	v_add_f32_e32 v161, v160, v161
	ds_bpermute_b32 v162, v159, v161
	v_cndmask_b32_e32 v160, v156, v166, vcc
	v_lshlrev_b32_e32 v160, 2, v160
	v_lshl_add_u64 v[164:165], s[10:11], 0, v[164:165]
	v_lshl_add_u64 v[164:165], v[164:165], 0, v[146:147]
	s_waitcnt lgkmcnt(0)
	v_add_f32_e32 v161, v161, v162
	ds_bpermute_b32 v166, v160, v161
	v_or_b32_e32 v162, 16, v148
	v_ashrrev_i32_e32 v163, 31, v162
	s_waitcnt lgkmcnt(0)
	v_add_f32_e32 v149, v161, v166
	v_fmamk_f32 v149, v149, 0x3a800000, v157
	v_lshlrev_b64 v[166:167], 6, v[162:163]
	v_lshl_add_u64 v[166:167], v[136:137], 0, v[166:167]
	v_rsq_f32_e32 v161, v149
	v_mul_f32_e32 v170, 0.5, v149
	v_mul_f32_e32 v168, v161, v161
	v_fma_f32 v170, -v170, v168, 0.5
	v_fma_f32 v168, v161, v170, v161
	v_pk_mul_f32 v[126:127], v[126:127], v[168:169] op_sel_hi:[1,0]
	v_pk_mul_f32 v[124:125], v[124:125], v[168:169] op_sel_hi:[1,0]
	v_pk_mul_f32 v[122:123], v[122:123], v[168:169] op_sel_hi:[1,0]
	v_pk_mul_f32 v[120:121], v[120:121], v[168:169] op_sel_hi:[1,0]
	v_pk_mul_f32 v[114:115], v[114:115], v[168:169] op_sel_hi:[1,0]
	v_pk_mul_f32 v[112:113], v[112:113], v[168:169] op_sel_hi:[1,0]
	v_pk_mul_f32 v[118:119], v[118:119], v[168:169] op_sel_hi:[1,0]
	v_pk_mul_f32 v[116:117], v[116:117], v[168:169] op_sel_hi:[1,0]
	v_max_f32_e32 v124, 0, v124
	v_max_f32_e32 v120, 0, v120
	v_max_f32_e32 v125, 0, v125
	v_max_f32_e32 v121, 0, v121
	v_max_f32_e32 v126, 0, v126
	v_max_f32_e32 v122, 0, v122
	v_max_f32_e32 v127, 0, v127
	v_max_f32_e32 v123, 0, v123
	v_max_f32_e32 v112, 0, v112
	v_max_f32_e32 v113, 0, v113
	v_max_f32_e32 v114, 0, v114
	v_max_f32_e32 v115, 0, v115
	v_max_f32_e32 v116, 0, v116
	v_max_f32_e32 v117, 0, v117
	v_max_f32_e32 v118, 0, v118
	v_max_f32_e32 v119, 0, v119
	v_mul_f32_e32 v124, v124, v124
	v_mul_f32_e32 v120, v120, v120
	v_mul_f32_e32 v125, v125, v125
	v_mul_f32_e32 v121, v121, v121
	v_mul_f32_e32 v126, v126, v126
	v_mul_f32_e32 v122, v122, v122
	v_mul_f32_e32 v127, v127, v127
	v_mul_f32_e32 v123, v123, v123
	v_mul_f32_e32 v149, v112, v112
	v_mul_f32_e32 v161, v113, v113
	v_mul_f32_e32 v168, v114, v114
	v_mul_f32_e32 v169, v115, v115
	v_cvt_pk_bf16_f32 v112, v124, v125
	v_cvt_pk_bf16_f32 v113, v126, v127
	v_cvt_pk_bf16_f32 v114, v120, v121
	v_cvt_pk_bf16_f32 v115, v122, v123
	v_mul_f32_e32 v116, v116, v116
	v_mul_f32_e32 v117, v117, v117
	v_mul_f32_e32 v118, v118, v118
	v_mul_f32_e32 v119, v119, v119
	global_store_dwordx4 v[164:165], v[112:115], off
	s_nop 1
	v_cvt_pk_bf16_f32 v112, v116, v117
	v_cvt_pk_bf16_f32 v113, v118, v119
	v_cvt_pk_bf16_f32 v114, v149, v161
	v_cvt_pk_bf16_f32 v115, v168, v169
	global_store_dwordx4 v[164:165], v[112:115], off offset:256
	s_waitcnt vmcnt(8)
	s_nop 1
	v_mov_b32_e32 v112, v206
	v_mov_b32_e32 v113, v207
	v_mov_b32_e32 v114, v208
	v_mov_b32_e32 v115, v209
	v_mov_b32_e32 v116, v113
	v_mov_b32_e32 v117, v114
	v_mov_b32_e32 v113, v115
	v_pk_add_f32 v[112:113], v[116:117], v[112:113]
	v_lshlrev_b64 v[114:115], 13, v[162:163]
	v_add_f32_e32 v112, v112, v113
	ds_bpermute_b32 v113, v159, v112
	v_lshl_add_u64 v[114:115], s[10:11], 0, v[114:115]
	v_lshl_add_u64 v[114:115], v[114:115], 0, v[146:147]
	s_waitcnt lgkmcnt(0)
	v_add_f32_e32 v116, v112, v113
	ds_bpermute_b32 v117, v160, v116
	v_or_b32_e32 v112, 32, v148
	v_ashrrev_i32_e32 v113, 31, v112
	s_waitcnt lgkmcnt(0)
	v_add_f32_e32 v116, v116, v117
	v_fmamk_f32 v116, v116, 0x3a800000, v157
	v_mov_b32_e32 v118, v116
	v_lshlrev_b64 v[116:117], 6, v[112:113]
	v_lshl_add_u64 v[116:117], v[136:137], 0, v[116:117]
	v_rsq_f32_e32 v119, v118
	v_mul_f32_e32 v120, 0.5, v118
	v_mul_f32_e32 v118, v119, v119
	v_fma_f32 v120, -v120, v118, 0.5
	v_fma_f32 v118, v119, v120, v119
	v_pk_mul_f32 v[110:111], v[110:111], v[118:119] op_sel_hi:[1,0]
	v_pk_mul_f32 v[108:109], v[108:109], v[118:119] op_sel_hi:[1,0]
	v_pk_mul_f32 v[106:107], v[106:107], v[118:119] op_sel_hi:[1,0]
	v_pk_mul_f32 v[104:105], v[104:105], v[118:119] op_sel_hi:[1,0]
	v_pk_mul_f32 v[98:99], v[98:99], v[118:119] op_sel_hi:[1,0]
	v_pk_mul_f32 v[96:97], v[96:97], v[118:119] op_sel_hi:[1,0]
	v_pk_mul_f32 v[102:103], v[102:103], v[118:119] op_sel_hi:[1,0]
	v_pk_mul_f32 v[100:101], v[100:101], v[118:119] op_sel_hi:[1,0]
	v_max_f32_e32 v108, 0, v108
	v_max_f32_e32 v104, 0, v104
	v_max_f32_e32 v109, 0, v109
	v_max_f32_e32 v105, 0, v105
	v_max_f32_e32 v110, 0, v110
	v_max_f32_e32 v106, 0, v106
	v_max_f32_e32 v111, 0, v111
	v_max_f32_e32 v107, 0, v107
	v_max_f32_e32 v96, 0, v96
	v_max_f32_e32 v97, 0, v97
	v_max_f32_e32 v98, 0, v98
	v_max_f32_e32 v99, 0, v99
	v_max_f32_e32 v100, 0, v100
	v_max_f32_e32 v101, 0, v101
	v_max_f32_e32 v102, 0, v102
	v_max_f32_e32 v103, 0, v103
	v_mul_f32_e32 v108, v108, v108
	v_mul_f32_e32 v104, v104, v104
	v_mul_f32_e32 v109, v109, v109
	v_mul_f32_e32 v105, v105, v105
	v_mul_f32_e32 v110, v110, v110
	v_mul_f32_e32 v106, v106, v106
	v_mul_f32_e32 v111, v111, v111
	v_mul_f32_e32 v107, v107, v107
	v_mul_f32_e32 v118, v96, v96
	v_mul_f32_e32 v119, v97, v97
	v_mul_f32_e32 v120, v98, v98
	v_mul_f32_e32 v121, v99, v99
	v_cvt_pk_bf16_f32 v96, v108, v109
	v_cvt_pk_bf16_f32 v97, v110, v111
	v_cvt_pk_bf16_f32 v98, v104, v105
	v_cvt_pk_bf16_f32 v99, v106, v107
	v_mul_f32_e32 v100, v100, v100
	v_mul_f32_e32 v101, v101, v101
	v_mul_f32_e32 v102, v102, v102
	v_mul_f32_e32 v103, v103, v103
	global_store_dwordx4 v[114:115], v[96:99], off
	s_nop 1
	v_cvt_pk_bf16_f32 v96, v100, v101
	v_cvt_pk_bf16_f32 v97, v102, v103
	v_cvt_pk_bf16_f32 v98, v118, v119
	v_cvt_pk_bf16_f32 v99, v120, v121
	global_store_dwordx4 v[114:115], v[96:99], off offset:256
	s_waitcnt vmcnt(9)
	s_nop 1
	v_mov_b32_e32 v96, v210
	v_mov_b32_e32 v97, v211
	v_mov_b32_e32 v98, v212
	v_mov_b32_e32 v99, v213
	v_mov_b32_e32 v100, v97
	v_mov_b32_e32 v101, v98
	v_mov_b32_e32 v97, v99
	v_pk_add_f32 v[96:97], v[100:101], v[96:97]
	v_lshlrev_b64 v[98:99], 13, v[112:113]
	v_add_f32_e32 v96, v96, v97
	ds_bpermute_b32 v97, v159, v96
	v_lshl_add_u64 v[98:99], s[10:11], 0, v[98:99]
	v_lshl_add_u64 v[98:99], v[98:99], 0, v[146:147]
	s_waitcnt lgkmcnt(0)
	v_add_f32_e32 v100, v96, v97
	ds_bpermute_b32 v101, v160, v100
	v_or_b32_e32 v96, 48, v148
	v_ashrrev_i32_e32 v97, 31, v96
	s_waitcnt lgkmcnt(0)
	v_add_f32_e32 v100, v100, v101
	v_fmamk_f32 v100, v100, 0x3a800000, v157
	v_mov_b32_e32 v102, v100
	v_lshlrev_b64 v[100:101], 6, v[96:97]
	v_lshl_add_u64 v[100:101], v[136:137], 0, v[100:101]
	v_rsq_f32_e32 v103, v102
	v_mul_f32_e32 v104, 0.5, v102
	v_mul_f32_e32 v102, v103, v103
	v_fma_f32 v104, -v104, v102, 0.5
	v_fma_f32 v102, v103, v104, v103
	v_pk_mul_f32 v[94:95], v[94:95], v[102:103] op_sel_hi:[1,0]
	v_pk_mul_f32 v[92:93], v[92:93], v[102:103] op_sel_hi:[1,0]
	v_pk_mul_f32 v[90:91], v[90:91], v[102:103] op_sel_hi:[1,0]
	v_pk_mul_f32 v[88:89], v[88:89], v[102:103] op_sel_hi:[1,0]
	v_pk_mul_f32 v[82:83], v[82:83], v[102:103] op_sel_hi:[1,0]
	v_pk_mul_f32 v[80:81], v[80:81], v[102:103] op_sel_hi:[1,0]
	v_pk_mul_f32 v[86:87], v[86:87], v[102:103] op_sel_hi:[1,0]
	v_pk_mul_f32 v[84:85], v[84:85], v[102:103] op_sel_hi:[1,0]
	v_max_f32_e32 v92, 0, v92
	v_max_f32_e32 v88, 0, v88
	v_max_f32_e32 v93, 0, v93
	v_max_f32_e32 v89, 0, v89
	v_max_f32_e32 v94, 0, v94
	v_max_f32_e32 v90, 0, v90
	v_max_f32_e32 v95, 0, v95
	v_max_f32_e32 v91, 0, v91
	v_max_f32_e32 v80, 0, v80
	v_max_f32_e32 v81, 0, v81
	v_max_f32_e32 v82, 0, v82
	v_max_f32_e32 v83, 0, v83
	v_max_f32_e32 v84, 0, v84
	v_max_f32_e32 v85, 0, v85
	v_max_f32_e32 v86, 0, v86
	v_max_f32_e32 v87, 0, v87
	v_mul_f32_e32 v92, v92, v92
	v_mul_f32_e32 v88, v88, v88
	v_mul_f32_e32 v93, v93, v93
	v_mul_f32_e32 v89, v89, v89
	v_mul_f32_e32 v94, v94, v94
	v_mul_f32_e32 v90, v90, v90
	v_mul_f32_e32 v95, v95, v95
	v_mul_f32_e32 v91, v91, v91
	v_mul_f32_e32 v102, v80, v80
	v_mul_f32_e32 v103, v81, v81
	v_mul_f32_e32 v104, v82, v82
	v_mul_f32_e32 v105, v83, v83
	v_cvt_pk_bf16_f32 v80, v92, v93
	v_cvt_pk_bf16_f32 v81, v94, v95
	v_cvt_pk_bf16_f32 v82, v88, v89
	v_cvt_pk_bf16_f32 v83, v90, v91
	v_mul_f32_e32 v84, v84, v84
	v_mul_f32_e32 v85, v85, v85
	v_mul_f32_e32 v86, v86, v86
	v_mul_f32_e32 v87, v87, v87
	global_store_dwordx4 v[98:99], v[80:83], off
	s_nop 1
	v_cvt_pk_bf16_f32 v80, v84, v85
	v_cvt_pk_bf16_f32 v81, v86, v87
	v_cvt_pk_bf16_f32 v82, v102, v103
	v_cvt_pk_bf16_f32 v83, v104, v105
	global_store_dwordx4 v[98:99], v[80:83], off offset:256
	s_waitcnt vmcnt(10)
	s_nop 1
	v_mov_b32_e32 v80, v214
	v_mov_b32_e32 v81, v215
	v_mov_b32_e32 v82, v216
	v_mov_b32_e32 v83, v217
	v_mov_b32_e32 v84, v81
	v_mov_b32_e32 v85, v82
	v_mov_b32_e32 v81, v83
	v_pk_add_f32 v[80:81], v[84:85], v[80:81]
	v_lshlrev_b64 v[82:83], 13, v[96:97]
	v_add_f32_e32 v80, v80, v81
	ds_bpermute_b32 v81, v159, v80
	v_lshl_add_u64 v[82:83], s[10:11], 0, v[82:83]
	v_lshl_add_u64 v[82:83], v[82:83], 0, v[146:147]
	s_waitcnt lgkmcnt(0)
	v_add_f32_e32 v84, v80, v81
	ds_bpermute_b32 v85, v160, v84
	v_add_u32_e32 v80, 0x80, v148
	v_ashrrev_i32_e32 v81, 31, v80
	s_waitcnt lgkmcnt(0)
	v_add_f32_e32 v84, v84, v85
	v_fmamk_f32 v84, v84, 0x3a800000, v157
	v_mov_b32_e32 v86, v84
	v_lshlrev_b64 v[84:85], 6, v[80:81]
	v_lshl_add_u64 v[84:85], v[136:137], 0, v[84:85]
	v_rsq_f32_e32 v87, v86
	v_mul_f32_e32 v88, 0.5, v86
	v_mul_f32_e32 v86, v87, v87
	v_fma_f32 v88, -v88, v86, 0.5
	v_fma_f32 v86, v87, v88, v87
	v_pk_mul_f32 v[78:79], v[78:79], v[86:87] op_sel_hi:[1,0]
	v_pk_mul_f32 v[76:77], v[76:77], v[86:87] op_sel_hi:[1,0]
	v_pk_mul_f32 v[74:75], v[74:75], v[86:87] op_sel_hi:[1,0]
	v_pk_mul_f32 v[72:73], v[72:73], v[86:87] op_sel_hi:[1,0]
	v_pk_mul_f32 v[66:67], v[66:67], v[86:87] op_sel_hi:[1,0]
	v_pk_mul_f32 v[64:65], v[64:65], v[86:87] op_sel_hi:[1,0]
	v_pk_mul_f32 v[70:71], v[70:71], v[86:87] op_sel_hi:[1,0]
	v_pk_mul_f32 v[68:69], v[68:69], v[86:87] op_sel_hi:[1,0]
	v_max_f32_e32 v76, 0, v76
	v_max_f32_e32 v72, 0, v72
	v_max_f32_e32 v77, 0, v77
	v_max_f32_e32 v73, 0, v73
	v_max_f32_e32 v78, 0, v78
	v_max_f32_e32 v74, 0, v74
	v_max_f32_e32 v79, 0, v79
	v_max_f32_e32 v75, 0, v75
	v_max_f32_e32 v64, 0, v64
	v_max_f32_e32 v65, 0, v65
	v_max_f32_e32 v66, 0, v66
	v_max_f32_e32 v67, 0, v67
	v_max_f32_e32 v68, 0, v68
	v_max_f32_e32 v69, 0, v69
	v_max_f32_e32 v70, 0, v70
	v_max_f32_e32 v71, 0, v71
	v_mul_f32_e32 v76, v76, v76
	v_mul_f32_e32 v72, v72, v72
	v_mul_f32_e32 v77, v77, v77
	v_mul_f32_e32 v73, v73, v73
	v_mul_f32_e32 v78, v78, v78
	v_mul_f32_e32 v74, v74, v74
	v_mul_f32_e32 v79, v79, v79
	v_mul_f32_e32 v75, v75, v75
	v_mul_f32_e32 v86, v64, v64
	v_mul_f32_e32 v87, v65, v65
	v_mul_f32_e32 v88, v66, v66
	v_mul_f32_e32 v89, v67, v67
	v_cvt_pk_bf16_f32 v64, v76, v77
	v_cvt_pk_bf16_f32 v65, v78, v79
	v_cvt_pk_bf16_f32 v66, v72, v73
	v_cvt_pk_bf16_f32 v67, v74, v75
	v_mul_f32_e32 v68, v68, v68
	v_mul_f32_e32 v69, v69, v69
	v_mul_f32_e32 v70, v70, v70
	v_mul_f32_e32 v71, v71, v71
	global_store_dwordx4 v[82:83], v[64:67], off
	s_nop 1
	v_cvt_pk_bf16_f32 v64, v68, v69
	v_cvt_pk_bf16_f32 v65, v70, v71
	v_cvt_pk_bf16_f32 v66, v86, v87
	v_cvt_pk_bf16_f32 v67, v88, v89
	global_store_dwordx4 v[82:83], v[64:67], off offset:256
	s_waitcnt vmcnt(11)
	s_nop 1
	v_mov_b32_e32 v64, v218
	v_mov_b32_e32 v65, v219
	v_mov_b32_e32 v66, v220
	v_mov_b32_e32 v67, v221
	v_mov_b32_e32 v68, v65
	v_mov_b32_e32 v69, v66
	v_mov_b32_e32 v65, v67
	v_pk_add_f32 v[64:65], v[68:69], v[64:65]
	v_lshlrev_b64 v[66:67], 13, v[80:81]
	v_add_f32_e32 v64, v64, v65
	ds_bpermute_b32 v65, v159, v64
	v_lshl_add_u64 v[66:67], s[10:11], 0, v[66:67]
	v_lshl_add_u64 v[66:67], v[66:67], 0, v[146:147]
	s_waitcnt lgkmcnt(0)
	v_add_f32_e32 v68, v64, v65
	ds_bpermute_b32 v69, v160, v68
	v_add_u32_e32 v64, 0x90, v148
	v_ashrrev_i32_e32 v65, 31, v64
	s_waitcnt lgkmcnt(0)
	v_add_f32_e32 v68, v68, v69
	v_fmamk_f32 v68, v68, 0x3a800000, v157
	v_mov_b32_e32 v70, v68
	v_lshlrev_b64 v[68:69], 6, v[64:65]
	v_lshl_add_u64 v[68:69], v[136:137], 0, v[68:69]
	v_rsq_f32_e32 v71, v70
	v_mul_f32_e32 v72, 0.5, v70
	v_mul_f32_e32 v70, v71, v71
	v_fma_f32 v72, -v72, v70, 0.5
	v_fma_f32 v70, v71, v72, v71
	v_pk_mul_f32 v[62:63], v[62:63], v[70:71] op_sel_hi:[1,0]
	v_pk_mul_f32 v[60:61], v[60:61], v[70:71] op_sel_hi:[1,0]
	v_pk_mul_f32 v[58:59], v[58:59], v[70:71] op_sel_hi:[1,0]
	v_pk_mul_f32 v[56:57], v[56:57], v[70:71] op_sel_hi:[1,0]
	v_pk_mul_f32 v[50:51], v[50:51], v[70:71] op_sel_hi:[1,0]
	v_pk_mul_f32 v[48:49], v[48:49], v[70:71] op_sel_hi:[1,0]
	v_pk_mul_f32 v[54:55], v[54:55], v[70:71] op_sel_hi:[1,0]
	v_pk_mul_f32 v[52:53], v[52:53], v[70:71] op_sel_hi:[1,0]
	v_max_f32_e32 v60, 0, v60
	v_max_f32_e32 v56, 0, v56
	v_max_f32_e32 v61, 0, v61
	v_max_f32_e32 v57, 0, v57
	v_max_f32_e32 v62, 0, v62
	v_max_f32_e32 v58, 0, v58
	v_max_f32_e32 v63, 0, v63
	v_max_f32_e32 v59, 0, v59
	v_max_f32_e32 v48, 0, v48
	v_max_f32_e32 v49, 0, v49
	v_max_f32_e32 v50, 0, v50
	v_max_f32_e32 v51, 0, v51
	v_max_f32_e32 v52, 0, v52
	v_max_f32_e32 v53, 0, v53
	v_max_f32_e32 v54, 0, v54
	v_max_f32_e32 v55, 0, v55
	v_mul_f32_e32 v60, v60, v60
	v_mul_f32_e32 v56, v56, v56
	v_mul_f32_e32 v61, v61, v61
	v_mul_f32_e32 v57, v57, v57
	v_mul_f32_e32 v62, v62, v62
	v_mul_f32_e32 v58, v58, v58
	v_mul_f32_e32 v63, v63, v63
	v_mul_f32_e32 v59, v59, v59
	v_mul_f32_e32 v70, v48, v48
	v_mul_f32_e32 v71, v49, v49
	v_mul_f32_e32 v72, v50, v50
	v_mul_f32_e32 v73, v51, v51
	v_cvt_pk_bf16_f32 v48, v60, v61
	v_cvt_pk_bf16_f32 v49, v62, v63
	v_cvt_pk_bf16_f32 v50, v56, v57
	v_cvt_pk_bf16_f32 v51, v58, v59
	v_mul_f32_e32 v52, v52, v52
	v_mul_f32_e32 v53, v53, v53
	v_mul_f32_e32 v54, v54, v54
	v_mul_f32_e32 v55, v55, v55
	global_store_dwordx4 v[66:67], v[48:51], off
	s_nop 1
	v_cvt_pk_bf16_f32 v48, v52, v53
	v_cvt_pk_bf16_f32 v49, v54, v55
	v_cvt_pk_bf16_f32 v50, v70, v71
	v_cvt_pk_bf16_f32 v51, v72, v73
	global_store_dwordx4 v[66:67], v[48:51], off offset:256
	s_waitcnt vmcnt(12)
	s_nop 1
	v_mov_b32_e32 v48, v222
	v_mov_b32_e32 v49, v223
	v_mov_b32_e32 v50, v224
	v_mov_b32_e32 v51, v225
	v_mov_b32_e32 v52, v49
	v_mov_b32_e32 v53, v50
	v_mov_b32_e32 v49, v51
	v_pk_add_f32 v[48:49], v[52:53], v[48:49]
	v_lshlrev_b64 v[50:51], 13, v[64:65]
	v_add_f32_e32 v48, v48, v49
	ds_bpermute_b32 v49, v159, v48
	v_lshl_add_u64 v[50:51], s[10:11], 0, v[50:51]
	v_lshl_add_u64 v[50:51], v[50:51], 0, v[146:147]
	s_waitcnt lgkmcnt(0)
	v_add_f32_e32 v52, v48, v49
	ds_bpermute_b32 v53, v160, v52
	v_add_u32_e32 v48, 0xa0, v148
	v_ashrrev_i32_e32 v49, 31, v48
	s_waitcnt lgkmcnt(0)
	v_add_f32_e32 v52, v52, v53
	v_fmamk_f32 v52, v52, 0x3a800000, v157
	v_mov_b32_e32 v54, v52
	v_lshlrev_b64 v[52:53], 6, v[48:49]
	v_lshl_add_u64 v[52:53], v[136:137], 0, v[52:53]
	v_rsq_f32_e32 v55, v54
	v_mul_f32_e32 v56, 0.5, v54
	v_mul_f32_e32 v54, v55, v55
	v_fma_f32 v56, -v56, v54, 0.5
	v_fma_f32 v54, v55, v56, v55
	v_pk_mul_f32 v[46:47], v[46:47], v[54:55] op_sel_hi:[1,0]
	v_pk_mul_f32 v[44:45], v[44:45], v[54:55] op_sel_hi:[1,0]
	v_pk_mul_f32 v[42:43], v[42:43], v[54:55] op_sel_hi:[1,0]
	v_pk_mul_f32 v[40:41], v[40:41], v[54:55] op_sel_hi:[1,0]
	v_pk_mul_f32 v[34:35], v[34:35], v[54:55] op_sel_hi:[1,0]
	v_pk_mul_f32 v[32:33], v[32:33], v[54:55] op_sel_hi:[1,0]
	v_pk_mul_f32 v[38:39], v[38:39], v[54:55] op_sel_hi:[1,0]
	v_pk_mul_f32 v[36:37], v[36:37], v[54:55] op_sel_hi:[1,0]
	v_max_f32_e32 v44, 0, v44
	v_max_f32_e32 v40, 0, v40
	v_max_f32_e32 v45, 0, v45
	v_max_f32_e32 v41, 0, v41
	v_max_f32_e32 v46, 0, v46
	v_max_f32_e32 v42, 0, v42
	v_max_f32_e32 v47, 0, v47
	v_max_f32_e32 v43, 0, v43
	v_max_f32_e32 v32, 0, v32
	v_max_f32_e32 v33, 0, v33
	v_max_f32_e32 v34, 0, v34
	v_max_f32_e32 v35, 0, v35
	v_max_f32_e32 v36, 0, v36
	v_max_f32_e32 v37, 0, v37
	v_max_f32_e32 v38, 0, v38
	v_max_f32_e32 v39, 0, v39
	v_mul_f32_e32 v44, v44, v44
	v_mul_f32_e32 v40, v40, v40
	v_mul_f32_e32 v45, v45, v45
	v_mul_f32_e32 v41, v41, v41
	v_mul_f32_e32 v46, v46, v46
	v_mul_f32_e32 v42, v42, v42
	v_mul_f32_e32 v47, v47, v47
	v_mul_f32_e32 v43, v43, v43
	v_mul_f32_e32 v54, v32, v32
	v_mul_f32_e32 v55, v33, v33
	v_mul_f32_e32 v56, v34, v34
	v_mul_f32_e32 v57, v35, v35
	v_cvt_pk_bf16_f32 v32, v44, v45
	v_cvt_pk_bf16_f32 v33, v46, v47
	v_cvt_pk_bf16_f32 v34, v40, v41
	v_cvt_pk_bf16_f32 v35, v42, v43
	v_mul_f32_e32 v36, v36, v36
	v_mul_f32_e32 v37, v37, v37
	v_mul_f32_e32 v38, v38, v38
	v_mul_f32_e32 v39, v39, v39
	global_store_dwordx4 v[50:51], v[32:35], off
	s_nop 1
	v_cvt_pk_bf16_f32 v32, v36, v37
	v_cvt_pk_bf16_f32 v33, v38, v39
	v_cvt_pk_bf16_f32 v34, v54, v55
	v_cvt_pk_bf16_f32 v35, v56, v57
	global_store_dwordx4 v[50:51], v[32:35], off offset:256
	s_waitcnt vmcnt(13)
	s_nop 1
	v_mov_b32_e32 v32, v226
	v_mov_b32_e32 v33, v227
	v_mov_b32_e32 v34, v228
	v_mov_b32_e32 v35, v229
	v_mov_b32_e32 v36, v33
	v_mov_b32_e32 v37, v34
	v_mov_b32_e32 v33, v35
	v_pk_add_f32 v[32:33], v[36:37], v[32:33]
	v_lshlrev_b64 v[34:35], 13, v[48:49]
	v_add_f32_e32 v32, v32, v33
	ds_bpermute_b32 v33, v159, v32
	v_lshl_add_u64 v[34:35], s[10:11], 0, v[34:35]
	v_lshl_add_u64 v[34:35], v[34:35], 0, v[146:147]
	s_waitcnt lgkmcnt(0)
	v_add_f32_e32 v36, v32, v33
	ds_bpermute_b32 v37, v160, v36
	v_add_u32_e32 v32, 0xb0, v148
	v_ashrrev_i32_e32 v33, 31, v32
	s_waitcnt lgkmcnt(0)
	v_add_f32_e32 v36, v36, v37
	v_fmamk_f32 v36, v36, 0x3a800000, v157
	v_mov_b32_e32 v38, v36
	v_lshlrev_b64 v[36:37], 6, v[32:33]
	v_lshl_add_u64 v[36:37], v[136:137], 0, v[36:37]
	v_rsq_f32_e32 v39, v38
	v_mul_f32_e32 v40, 0.5, v38
	v_mul_f32_e32 v38, v39, v39
	v_fma_f32 v40, -v40, v38, 0.5
	v_fma_f32 v38, v39, v40, v39
	v_pk_mul_f32 v[30:31], v[30:31], v[38:39] op_sel_hi:[1,0]
	v_pk_mul_f32 v[28:29], v[28:29], v[38:39] op_sel_hi:[1,0]
	v_pk_mul_f32 v[26:27], v[26:27], v[38:39] op_sel_hi:[1,0]
	v_pk_mul_f32 v[24:25], v[24:25], v[38:39] op_sel_hi:[1,0]
	v_pk_mul_f32 v[18:19], v[18:19], v[38:39] op_sel_hi:[1,0]
	v_pk_mul_f32 v[16:17], v[16:17], v[38:39] op_sel_hi:[1,0]
	v_pk_mul_f32 v[22:23], v[22:23], v[38:39] op_sel_hi:[1,0]
	v_pk_mul_f32 v[20:21], v[20:21], v[38:39] op_sel_hi:[1,0]
	v_max_f32_e32 v28, 0, v28
	v_max_f32_e32 v24, 0, v24
	v_max_f32_e32 v29, 0, v29
	v_max_f32_e32 v25, 0, v25
	v_max_f32_e32 v30, 0, v30
	v_max_f32_e32 v26, 0, v26
	v_max_f32_e32 v31, 0, v31
	v_max_f32_e32 v27, 0, v27
	v_max_f32_e32 v16, 0, v16
	v_max_f32_e32 v17, 0, v17
	v_max_f32_e32 v18, 0, v18
	v_max_f32_e32 v19, 0, v19
	v_max_f32_e32 v20, 0, v20
	v_max_f32_e32 v21, 0, v21
	v_max_f32_e32 v22, 0, v22
	v_max_f32_e32 v23, 0, v23
	v_mul_f32_e32 v28, v28, v28
	v_mul_f32_e32 v24, v24, v24
	v_mul_f32_e32 v29, v29, v29
	v_mul_f32_e32 v25, v25, v25
	v_mul_f32_e32 v30, v30, v30
	v_mul_f32_e32 v26, v26, v26
	v_mul_f32_e32 v31, v31, v31
	v_mul_f32_e32 v27, v27, v27
	v_mul_f32_e32 v38, v16, v16
	v_mul_f32_e32 v39, v17, v17
	v_mul_f32_e32 v40, v18, v18
	v_mul_f32_e32 v41, v19, v19
	v_cvt_pk_bf16_f32 v16, v28, v29
	v_cvt_pk_bf16_f32 v17, v30, v31
	v_cvt_pk_bf16_f32 v18, v24, v25
	v_cvt_pk_bf16_f32 v19, v26, v27
	v_mul_f32_e32 v20, v20, v20
	v_mul_f32_e32 v21, v21, v21
	v_mul_f32_e32 v22, v22, v22
	v_mul_f32_e32 v23, v23, v23
	global_store_dwordx4 v[34:35], v[16:19], off
	s_nop 1
	v_cvt_pk_bf16_f32 v16, v20, v21
	v_cvt_pk_bf16_f32 v17, v22, v23
	v_cvt_pk_bf16_f32 v18, v38, v39
	v_cvt_pk_bf16_f32 v19, v40, v41
	global_store_dwordx4 v[34:35], v[16:19], off offset:256
	s_waitcnt vmcnt(14)
	s_nop 1
	v_mov_b32_e32 v16, v230
	v_mov_b32_e32 v17, v231
	v_mov_b32_e32 v18, v232
	v_mov_b32_e32 v19, v233
	v_mov_b32_e32 v20, v17
	v_mov_b32_e32 v21, v18
	v_mov_b32_e32 v17, v19
	v_pk_add_f32 v[16:17], v[20:21], v[16:17]
	s_nop 0
	v_add_f32_e32 v16, v16, v17
	ds_bpermute_b32 v17, v159, v16
	s_waitcnt lgkmcnt(0)
	v_add_f32_e32 v16, v16, v17
	ds_bpermute_b32 v17, v160, v16
	s_waitcnt lgkmcnt(0)
	v_add_f32_e32 v16, v16, v17
	v_fmamk_f32 v16, v16, 0x3a800000, v157
	v_mov_b32_e32 v18, v16
	v_lshlrev_b64 v[16:17], 13, v[32:33]
	v_lshl_add_u64 v[16:17], s[10:11], 0, v[16:17]
	v_lshl_add_u64 v[16:17], v[16:17], 0, v[146:147]
	v_rsq_f32_e32 v19, v18
	v_mul_f32_e32 v20, 0.5, v18
	v_mul_f32_e32 v18, v19, v19
	v_fma_f32 v20, -v20, v18, 0.5
	v_fma_f32 v18, v19, v20, v19
	v_pk_mul_f32 v[14:15], v[14:15], v[18:19] op_sel_hi:[1,0]
	v_pk_mul_f32 v[12:13], v[12:13], v[18:19] op_sel_hi:[1,0]
	v_pk_mul_f32 v[10:11], v[10:11], v[18:19] op_sel_hi:[1,0]
	v_pk_mul_f32 v[8:9], v[8:9], v[18:19] op_sel_hi:[1,0]
	v_pk_mul_f32 v[2:3], v[2:3], v[18:19] op_sel_hi:[1,0]
	v_pk_mul_f32 v[0:1], v[0:1], v[18:19] op_sel_hi:[1,0]
	v_pk_mul_f32 v[6:7], v[6:7], v[18:19] op_sel_hi:[1,0]
	v_pk_mul_f32 v[4:5], v[4:5], v[18:19] op_sel_hi:[1,0]
	v_max_f32_e32 v12, 0, v12
	v_max_f32_e32 v8, 0, v8
	v_max_f32_e32 v13, 0, v13
	v_max_f32_e32 v9, 0, v9
	v_max_f32_e32 v14, 0, v14
	v_max_f32_e32 v10, 0, v10
	v_max_f32_e32 v15, 0, v15
	v_max_f32_e32 v11, 0, v11
	v_max_f32_e32 v0, 0, v0
	v_max_f32_e32 v1, 0, v1
	v_max_f32_e32 v2, 0, v2
	v_max_f32_e32 v3, 0, v3
	s_andn2_b64 vcc, exec, s[0:1]
	v_max_f32_e32 v4, 0, v4
	v_max_f32_e32 v5, 0, v5
	v_max_f32_e32 v6, 0, v6
	v_max_f32_e32 v7, 0, v7
	v_mul_f32_e32 v12, v12, v12
	v_mul_f32_e32 v8, v8, v8
	v_mul_f32_e32 v13, v13, v13
	v_mul_f32_e32 v9, v9, v9
	v_mul_f32_e32 v14, v14, v14
	v_mul_f32_e32 v10, v10, v10
	v_mul_f32_e32 v15, v15, v15
	v_mul_f32_e32 v11, v11, v11
	v_mul_f32_e32 v18, v0, v0
	v_mul_f32_e32 v19, v1, v1
	v_mul_f32_e32 v20, v2, v2
	v_mul_f32_e32 v21, v3, v3
	v_cvt_pk_bf16_f32 v0, v12, v13
	v_cvt_pk_bf16_f32 v1, v14, v15
	v_cvt_pk_bf16_f32 v2, v8, v9
	v_cvt_pk_bf16_f32 v3, v10, v11
	s_mov_b64 s[0:1], -1
	v_mul_f32_e32 v4, v4, v4
	v_mul_f32_e32 v5, v5, v5
	v_mul_f32_e32 v6, v6, v6
	v_mul_f32_e32 v7, v7, v7
	global_store_dwordx4 v[16:17], v[0:3], off
	s_nop 1
	v_cvt_pk_bf16_f32 v0, v4, v5
	v_cvt_pk_bf16_f32 v1, v6, v7
	v_cvt_pk_bf16_f32 v2, v18, v19
	v_cvt_pk_bf16_f32 v3, v20, v21
	global_store_dwordx4 v[16:17], v[0:3], off offset:256
	s_cbranch_vccnz .LBB0_768
	s_andn2_b64 vcc, exec, s[8:9]
	s_cbranch_vccnz .LBB0_767
	s_barrier
	s_branch .LBB0_767

.LBB0_1252:
	v_lshl_add_u32 v148, s4, 8, v150
	v_ashrrev_i32_e32 v149, 31, v148
	v_lshlrev_b64 v[146:147], 6, v[148:149]
	v_lshl_add_u64 v[146:147], v[136:137], 0, v[146:147]
	s_mov_b64 s[98:99], 0x2000
	global_load_dwordx4 v[160:163], v[146:147], off
	global_load_dwordx4 v[206:209], v[146:147], off offset:1024
	global_load_dwordx4 v[210:213], v[146:147], off offset:2048
	global_load_dwordx4 v[214:217], v[146:147], off offset:3072
	v_lshl_add_u64 v[194:195], v[146:147], 0, s[98:99]
	global_load_dwordx4 v[218:221], v[194:195], off
	global_load_dwordx4 v[222:225], v[194:195], off offset:1024
	global_load_dwordx4 v[226:229], v[194:195], off offset:2048
	global_load_dwordx4 v[230:233], v[194:195], off offset:3072
	v_and_b32_e32 v159, 64, v156
	v_xor_b32_e32 v147, 16, v156
	v_add_u32_e32 v167, 64, v159
	v_cmp_lt_i32_e32 vcc, v147, v167
	v_xor_b32_e32 v166, 32, v156
	v_lshl_or_b32 v146, s5, 8, v152
	v_cndmask_b32_e32 v147, v156, v147, vcc
	v_lshlrev_b32_e32 v159, 2, v147
	v_cmp_lt_i32_e32 vcc, v166, v167
	v_ashrrev_i32_e32 v147, 31, v146
	v_lshlrev_b64 v[146:147], 1, v[146:147]
	s_waitcnt vmcnt(7)
	v_mov_b32_e32 v164, v161
	v_mov_b32_e32 v165, v162
	v_mov_b32_e32 v161, v163
	v_pk_add_f32 v[160:161], v[164:165], v[160:161]
	v_lshlrev_b64 v[164:165], 13, v[148:149]
	v_add_f32_e32 v161, v160, v161
	ds_bpermute_b32 v162, v159, v161
	v_cndmask_b32_e32 v160, v156, v166, vcc
	v_lshlrev_b32_e32 v160, 2, v160
	v_lshl_add_u64 v[164:165], s[10:11], 0, v[164:165]
	v_lshl_add_u64 v[164:165], v[164:165], 0, v[146:147]
	s_waitcnt lgkmcnt(0)
	v_add_f32_e32 v161, v161, v162
	ds_bpermute_b32 v166, v160, v161
	v_or_b32_e32 v162, 16, v148
	v_ashrrev_i32_e32 v163, 31, v162
	s_waitcnt lgkmcnt(0)
	v_add_f32_e32 v149, v161, v166
	v_fmamk_f32 v149, v149, 0x3a800000, v157
	v_lshlrev_b64 v[166:167], 6, v[162:163]
	v_lshl_add_u64 v[166:167], v[136:137], 0, v[166:167]
	v_rsq_f32_e32 v161, v149
	v_mul_f32_e32 v170, 0.5, v149
	v_mul_f32_e32 v168, v161, v161
	v_fma_f32 v170, -v170, v168, 0.5
	v_fma_f32 v168, v161, v170, v161
	v_pk_mul_f32 v[126:127], v[126:127], v[168:169] op_sel_hi:[1,0]
	v_pk_mul_f32 v[124:125], v[124:125], v[168:169] op_sel_hi:[1,0]
	v_pk_mul_f32 v[122:123], v[122:123], v[168:169] op_sel_hi:[1,0]
	v_pk_mul_f32 v[120:121], v[120:121], v[168:169] op_sel_hi:[1,0]
	v_pk_mul_f32 v[114:115], v[114:115], v[168:169] op_sel_hi:[1,0]
	v_pk_mul_f32 v[112:113], v[112:113], v[168:169] op_sel_hi:[1,0]
	v_pk_mul_f32 v[118:119], v[118:119], v[168:169] op_sel_hi:[1,0]
	v_pk_mul_f32 v[116:117], v[116:117], v[168:169] op_sel_hi:[1,0]
	v_max_f32_e32 v124, 0, v124
	v_max_f32_e32 v120, 0, v120
	v_max_f32_e32 v125, 0, v125
	v_max_f32_e32 v121, 0, v121
	v_max_f32_e32 v126, 0, v126
	v_max_f32_e32 v122, 0, v122
	v_max_f32_e32 v127, 0, v127
	v_max_f32_e32 v123, 0, v123
	v_max_f32_e32 v112, 0, v112
	v_max_f32_e32 v113, 0, v113
	v_max_f32_e32 v114, 0, v114
	v_max_f32_e32 v115, 0, v115
	v_max_f32_e32 v116, 0, v116
	v_max_f32_e32 v117, 0, v117
	v_max_f32_e32 v118, 0, v118
	v_max_f32_e32 v119, 0, v119
	v_mul_f32_e32 v124, v124, v124
	v_mul_f32_e32 v120, v120, v120
	v_mul_f32_e32 v125, v125, v125
	v_mul_f32_e32 v121, v121, v121
	v_mul_f32_e32 v126, v126, v126
	v_mul_f32_e32 v122, v122, v122
	v_mul_f32_e32 v127, v127, v127
	v_mul_f32_e32 v123, v123, v123
	v_mul_f32_e32 v149, v112, v112
	v_mul_f32_e32 v161, v113, v113
	v_mul_f32_e32 v168, v114, v114
	v_mul_f32_e32 v169, v115, v115
	v_cvt_pk_bf16_f32 v112, v124, v125
	v_cvt_pk_bf16_f32 v113, v126, v127
	v_cvt_pk_bf16_f32 v114, v120, v121
	v_cvt_pk_bf16_f32 v115, v122, v123
	v_mul_f32_e32 v116, v116, v116
	v_mul_f32_e32 v117, v117, v117
	v_mul_f32_e32 v118, v118, v118
	v_mul_f32_e32 v119, v119, v119
	global_store_dwordx4 v[164:165], v[112:115], off
	s_nop 1
	v_cvt_pk_bf16_f32 v112, v116, v117
	v_cvt_pk_bf16_f32 v113, v118, v119
	v_cvt_pk_bf16_f32 v114, v149, v161
	v_cvt_pk_bf16_f32 v115, v168, v169
	global_store_dwordx4 v[164:165], v[112:115], off offset:256
	s_waitcnt vmcnt(8)
	s_nop 1
	v_mov_b32_e32 v112, v206
	v_mov_b32_e32 v113, v207
	v_mov_b32_e32 v114, v208
	v_mov_b32_e32 v115, v209
	v_mov_b32_e32 v116, v113
	v_mov_b32_e32 v117, v114
	v_mov_b32_e32 v113, v115
	v_pk_add_f32 v[112:113], v[116:117], v[112:113]
	v_lshlrev_b64 v[114:115], 13, v[162:163]
	v_add_f32_e32 v112, v112, v113
	ds_bpermute_b32 v113, v159, v112
	v_lshl_add_u64 v[114:115], s[10:11], 0, v[114:115]
	v_lshl_add_u64 v[114:115], v[114:115], 0, v[146:147]
	s_waitcnt lgkmcnt(0)
	v_add_f32_e32 v116, v112, v113
	ds_bpermute_b32 v117, v160, v116
	v_or_b32_e32 v112, 32, v148
	v_ashrrev_i32_e32 v113, 31, v112
	s_waitcnt lgkmcnt(0)
	v_add_f32_e32 v116, v116, v117
	v_fmamk_f32 v116, v116, 0x3a800000, v157
	v_mov_b32_e32 v118, v116
	v_lshlrev_b64 v[116:117], 6, v[112:113]
	v_lshl_add_u64 v[116:117], v[136:137], 0, v[116:117]
	v_rsq_f32_e32 v119, v118
	v_mul_f32_e32 v120, 0.5, v118
	v_mul_f32_e32 v118, v119, v119
	v_fma_f32 v120, -v120, v118, 0.5
	v_fma_f32 v118, v119, v120, v119
	v_pk_mul_f32 v[110:111], v[110:111], v[118:119] op_sel_hi:[1,0]
	v_pk_mul_f32 v[108:109], v[108:109], v[118:119] op_sel_hi:[1,0]
	v_pk_mul_f32 v[106:107], v[106:107], v[118:119] op_sel_hi:[1,0]
	v_pk_mul_f32 v[104:105], v[104:105], v[118:119] op_sel_hi:[1,0]
	v_pk_mul_f32 v[98:99], v[98:99], v[118:119] op_sel_hi:[1,0]
	v_pk_mul_f32 v[96:97], v[96:97], v[118:119] op_sel_hi:[1,0]
	v_pk_mul_f32 v[102:103], v[102:103], v[118:119] op_sel_hi:[1,0]
	v_pk_mul_f32 v[100:101], v[100:101], v[118:119] op_sel_hi:[1,0]
	v_max_f32_e32 v108, 0, v108
	v_max_f32_e32 v104, 0, v104
	v_max_f32_e32 v109, 0, v109
	v_max_f32_e32 v105, 0, v105
	v_max_f32_e32 v110, 0, v110
	v_max_f32_e32 v106, 0, v106
	v_max_f32_e32 v111, 0, v111
	v_max_f32_e32 v107, 0, v107
	v_max_f32_e32 v96, 0, v96
	v_max_f32_e32 v97, 0, v97
	v_max_f32_e32 v98, 0, v98
	v_max_f32_e32 v99, 0, v99
	v_max_f32_e32 v100, 0, v100
	v_max_f32_e32 v101, 0, v101
	v_max_f32_e32 v102, 0, v102
	v_max_f32_e32 v103, 0, v103
	v_mul_f32_e32 v108, v108, v108
	v_mul_f32_e32 v104, v104, v104
	v_mul_f32_e32 v109, v109, v109
	v_mul_f32_e32 v105, v105, v105
	v_mul_f32_e32 v110, v110, v110
	v_mul_f32_e32 v106, v106, v106
	v_mul_f32_e32 v111, v111, v111
	v_mul_f32_e32 v107, v107, v107
	v_mul_f32_e32 v118, v96, v96
	v_mul_f32_e32 v119, v97, v97
	v_mul_f32_e32 v120, v98, v98
	v_mul_f32_e32 v121, v99, v99
	v_cvt_pk_bf16_f32 v96, v108, v109
	v_cvt_pk_bf16_f32 v97, v110, v111
	v_cvt_pk_bf16_f32 v98, v104, v105
	v_cvt_pk_bf16_f32 v99, v106, v107
	v_mul_f32_e32 v100, v100, v100
	v_mul_f32_e32 v101, v101, v101
	v_mul_f32_e32 v102, v102, v102
	v_mul_f32_e32 v103, v103, v103
	global_store_dwordx4 v[114:115], v[96:99], off
	s_nop 1
	v_cvt_pk_bf16_f32 v96, v100, v101
	v_cvt_pk_bf16_f32 v97, v102, v103
	v_cvt_pk_bf16_f32 v98, v118, v119
	v_cvt_pk_bf16_f32 v99, v120, v121
	global_store_dwordx4 v[114:115], v[96:99], off offset:256
	s_waitcnt vmcnt(9)
	s_nop 1
	v_mov_b32_e32 v96, v210
	v_mov_b32_e32 v97, v211
	v_mov_b32_e32 v98, v212
	v_mov_b32_e32 v99, v213
	v_mov_b32_e32 v100, v97
	v_mov_b32_e32 v101, v98
	v_mov_b32_e32 v97, v99
	v_pk_add_f32 v[96:97], v[100:101], v[96:97]
	v_lshlrev_b64 v[98:99], 13, v[112:113]
	v_add_f32_e32 v96, v96, v97
	ds_bpermute_b32 v97, v159, v96
	v_lshl_add_u64 v[98:99], s[10:11], 0, v[98:99]
	v_lshl_add_u64 v[98:99], v[98:99], 0, v[146:147]
	s_waitcnt lgkmcnt(0)
	v_add_f32_e32 v100, v96, v97
	ds_bpermute_b32 v101, v160, v100
	v_or_b32_e32 v96, 48, v148
	v_ashrrev_i32_e32 v97, 31, v96
	s_waitcnt lgkmcnt(0)
	v_add_f32_e32 v100, v100, v101
	v_fmamk_f32 v100, v100, 0x3a800000, v157
	v_mov_b32_e32 v102, v100
	v_lshlrev_b64 v[100:101], 6, v[96:97]
	v_lshl_add_u64 v[100:101], v[136:137], 0, v[100:101]
	v_rsq_f32_e32 v103, v102
	v_mul_f32_e32 v104, 0.5, v102
	v_mul_f32_e32 v102, v103, v103
	v_fma_f32 v104, -v104, v102, 0.5
	v_fma_f32 v102, v103, v104, v103
	v_pk_mul_f32 v[94:95], v[94:95], v[102:103] op_sel_hi:[1,0]
	v_pk_mul_f32 v[92:93], v[92:93], v[102:103] op_sel_hi:[1,0]
	v_pk_mul_f32 v[90:91], v[90:91], v[102:103] op_sel_hi:[1,0]
	v_pk_mul_f32 v[88:89], v[88:89], v[102:103] op_sel_hi:[1,0]
	v_pk_mul_f32 v[82:83], v[82:83], v[102:103] op_sel_hi:[1,0]
	v_pk_mul_f32 v[80:81], v[80:81], v[102:103] op_sel_hi:[1,0]
	v_pk_mul_f32 v[86:87], v[86:87], v[102:103] op_sel_hi:[1,0]
	v_pk_mul_f32 v[84:85], v[84:85], v[102:103] op_sel_hi:[1,0]
	v_max_f32_e32 v92, 0, v92
	v_max_f32_e32 v88, 0, v88
	v_max_f32_e32 v93, 0, v93
	v_max_f32_e32 v89, 0, v89
	v_max_f32_e32 v94, 0, v94
	v_max_f32_e32 v90, 0, v90
	v_max_f32_e32 v95, 0, v95
	v_max_f32_e32 v91, 0, v91
	v_max_f32_e32 v80, 0, v80
	v_max_f32_e32 v81, 0, v81
	v_max_f32_e32 v82, 0, v82
	v_max_f32_e32 v83, 0, v83
	v_max_f32_e32 v84, 0, v84
	v_max_f32_e32 v85, 0, v85
	v_max_f32_e32 v86, 0, v86
	v_max_f32_e32 v87, 0, v87
	v_mul_f32_e32 v92, v92, v92
	v_mul_f32_e32 v88, v88, v88
	v_mul_f32_e32 v93, v93, v93
	v_mul_f32_e32 v89, v89, v89
	v_mul_f32_e32 v94, v94, v94
	v_mul_f32_e32 v90, v90, v90
	v_mul_f32_e32 v95, v95, v95
	v_mul_f32_e32 v91, v91, v91
	v_mul_f32_e32 v102, v80, v80
	v_mul_f32_e32 v103, v81, v81
	v_mul_f32_e32 v104, v82, v82
	v_mul_f32_e32 v105, v83, v83
	v_cvt_pk_bf16_f32 v80, v92, v93
	v_cvt_pk_bf16_f32 v81, v94, v95
	v_cvt_pk_bf16_f32 v82, v88, v89
	v_cvt_pk_bf16_f32 v83, v90, v91
	v_mul_f32_e32 v84, v84, v84
	v_mul_f32_e32 v85, v85, v85
	v_mul_f32_e32 v86, v86, v86
	v_mul_f32_e32 v87, v87, v87
	global_store_dwordx4 v[98:99], v[80:83], off
	s_nop 1
	v_cvt_pk_bf16_f32 v80, v84, v85
	v_cvt_pk_bf16_f32 v81, v86, v87
	v_cvt_pk_bf16_f32 v82, v102, v103
	v_cvt_pk_bf16_f32 v83, v104, v105
	global_store_dwordx4 v[98:99], v[80:83], off offset:256
	s_waitcnt vmcnt(10)
	s_nop 1
	v_mov_b32_e32 v80, v214
	v_mov_b32_e32 v81, v215
	v_mov_b32_e32 v82, v216
	v_mov_b32_e32 v83, v217
	v_mov_b32_e32 v84, v81
	v_mov_b32_e32 v85, v82
	v_mov_b32_e32 v81, v83
	v_pk_add_f32 v[80:81], v[84:85], v[80:81]
	v_lshlrev_b64 v[82:83], 13, v[96:97]
	v_add_f32_e32 v80, v80, v81
	ds_bpermute_b32 v81, v159, v80
	v_lshl_add_u64 v[82:83], s[10:11], 0, v[82:83]
	v_lshl_add_u64 v[82:83], v[82:83], 0, v[146:147]
	s_waitcnt lgkmcnt(0)
	v_add_f32_e32 v84, v80, v81
	ds_bpermute_b32 v85, v160, v84
	v_add_u32_e32 v80, 0x80, v148
	v_ashrrev_i32_e32 v81, 31, v80
	s_waitcnt lgkmcnt(0)
	v_add_f32_e32 v84, v84, v85
	v_fmamk_f32 v84, v84, 0x3a800000, v157
	v_mov_b32_e32 v86, v84
	v_lshlrev_b64 v[84:85], 6, v[80:81]
	v_lshl_add_u64 v[84:85], v[136:137], 0, v[84:85]
	v_rsq_f32_e32 v87, v86
	v_mul_f32_e32 v88, 0.5, v86
	v_mul_f32_e32 v86, v87, v87
	v_fma_f32 v88, -v88, v86, 0.5
	v_fma_f32 v86, v87, v88, v87
	v_pk_mul_f32 v[78:79], v[78:79], v[86:87] op_sel_hi:[1,0]
	v_pk_mul_f32 v[76:77], v[76:77], v[86:87] op_sel_hi:[1,0]
	v_pk_mul_f32 v[74:75], v[74:75], v[86:87] op_sel_hi:[1,0]
	v_pk_mul_f32 v[72:73], v[72:73], v[86:87] op_sel_hi:[1,0]
	v_pk_mul_f32 v[66:67], v[66:67], v[86:87] op_sel_hi:[1,0]
	v_pk_mul_f32 v[64:65], v[64:65], v[86:87] op_sel_hi:[1,0]
	v_pk_mul_f32 v[70:71], v[70:71], v[86:87] op_sel_hi:[1,0]
	v_pk_mul_f32 v[68:69], v[68:69], v[86:87] op_sel_hi:[1,0]
	v_max_f32_e32 v76, 0, v76
	v_max_f32_e32 v72, 0, v72
	v_max_f32_e32 v77, 0, v77
	v_max_f32_e32 v73, 0, v73
	v_max_f32_e32 v78, 0, v78
	v_max_f32_e32 v74, 0, v74
	v_max_f32_e32 v79, 0, v79
	v_max_f32_e32 v75, 0, v75
	v_max_f32_e32 v64, 0, v64
	v_max_f32_e32 v65, 0, v65
	v_max_f32_e32 v66, 0, v66
	v_max_f32_e32 v67, 0, v67
	v_max_f32_e32 v68, 0, v68
	v_max_f32_e32 v69, 0, v69
	v_max_f32_e32 v70, 0, v70
	v_max_f32_e32 v71, 0, v71
	v_mul_f32_e32 v76, v76, v76
	v_mul_f32_e32 v72, v72, v72
	v_mul_f32_e32 v77, v77, v77
	v_mul_f32_e32 v73, v73, v73
	v_mul_f32_e32 v78, v78, v78
	v_mul_f32_e32 v74, v74, v74
	v_mul_f32_e32 v79, v79, v79
	v_mul_f32_e32 v75, v75, v75
	v_mul_f32_e32 v86, v64, v64
	v_mul_f32_e32 v87, v65, v65
	v_mul_f32_e32 v88, v66, v66
	v_mul_f32_e32 v89, v67, v67
	v_cvt_pk_bf16_f32 v64, v76, v77
	v_cvt_pk_bf16_f32 v65, v78, v79
	v_cvt_pk_bf16_f32 v66, v72, v73
	v_cvt_pk_bf16_f32 v67, v74, v75
	v_mul_f32_e32 v68, v68, v68
	v_mul_f32_e32 v69, v69, v69
	v_mul_f32_e32 v70, v70, v70
	v_mul_f32_e32 v71, v71, v71
	global_store_dwordx4 v[82:83], v[64:67], off
	s_nop 1
	v_cvt_pk_bf16_f32 v64, v68, v69
	v_cvt_pk_bf16_f32 v65, v70, v71
	v_cvt_pk_bf16_f32 v66, v86, v87
	v_cvt_pk_bf16_f32 v67, v88, v89
	global_store_dwordx4 v[82:83], v[64:67], off offset:256
	s_waitcnt vmcnt(11)
	s_nop 1
	v_mov_b32_e32 v64, v218
	v_mov_b32_e32 v65, v219
	v_mov_b32_e32 v66, v220
	v_mov_b32_e32 v67, v221
	v_mov_b32_e32 v68, v65
	v_mov_b32_e32 v69, v66
	v_mov_b32_e32 v65, v67
	v_pk_add_f32 v[64:65], v[68:69], v[64:65]
	v_lshlrev_b64 v[66:67], 13, v[80:81]
	v_add_f32_e32 v64, v64, v65
	ds_bpermute_b32 v65, v159, v64
	v_lshl_add_u64 v[66:67], s[10:11], 0, v[66:67]
	v_lshl_add_u64 v[66:67], v[66:67], 0, v[146:147]
	s_waitcnt lgkmcnt(0)
	v_add_f32_e32 v68, v64, v65
	ds_bpermute_b32 v69, v160, v68
	v_add_u32_e32 v64, 0x90, v148
	v_ashrrev_i32_e32 v65, 31, v64
	s_waitcnt lgkmcnt(0)
	v_add_f32_e32 v68, v68, v69
	v_fmamk_f32 v68, v68, 0x3a800000, v157
	v_mov_b32_e32 v70, v68
	v_lshlrev_b64 v[68:69], 6, v[64:65]
	v_lshl_add_u64 v[68:69], v[136:137], 0, v[68:69]
	v_rsq_f32_e32 v71, v70
	v_mul_f32_e32 v72, 0.5, v70
	v_mul_f32_e32 v70, v71, v71
	v_fma_f32 v72, -v72, v70, 0.5
	v_fma_f32 v70, v71, v72, v71
	v_pk_mul_f32 v[62:63], v[62:63], v[70:71] op_sel_hi:[1,0]
	v_pk_mul_f32 v[60:61], v[60:61], v[70:71] op_sel_hi:[1,0]
	v_pk_mul_f32 v[58:59], v[58:59], v[70:71] op_sel_hi:[1,0]
	v_pk_mul_f32 v[56:57], v[56:57], v[70:71] op_sel_hi:[1,0]
	v_pk_mul_f32 v[50:51], v[50:51], v[70:71] op_sel_hi:[1,0]
	v_pk_mul_f32 v[48:49], v[48:49], v[70:71] op_sel_hi:[1,0]
	v_pk_mul_f32 v[54:55], v[54:55], v[70:71] op_sel_hi:[1,0]
	v_pk_mul_f32 v[52:53], v[52:53], v[70:71] op_sel_hi:[1,0]
	v_max_f32_e32 v60, 0, v60
	v_max_f32_e32 v56, 0, v56
	v_max_f32_e32 v61, 0, v61
	v_max_f32_e32 v57, 0, v57
	v_max_f32_e32 v62, 0, v62
	v_max_f32_e32 v58, 0, v58
	v_max_f32_e32 v63, 0, v63
	v_max_f32_e32 v59, 0, v59
	v_max_f32_e32 v48, 0, v48
	v_max_f32_e32 v49, 0, v49
	v_max_f32_e32 v50, 0, v50
	v_max_f32_e32 v51, 0, v51
	v_max_f32_e32 v52, 0, v52
	v_max_f32_e32 v53, 0, v53
	v_max_f32_e32 v54, 0, v54
	v_max_f32_e32 v55, 0, v55
	v_mul_f32_e32 v60, v60, v60
	v_mul_f32_e32 v56, v56, v56
	v_mul_f32_e32 v61, v61, v61
	v_mul_f32_e32 v57, v57, v57
	v_mul_f32_e32 v62, v62, v62
	v_mul_f32_e32 v58, v58, v58
	v_mul_f32_e32 v63, v63, v63
	v_mul_f32_e32 v59, v59, v59
	v_mul_f32_e32 v70, v48, v48
	v_mul_f32_e32 v71, v49, v49
	v_mul_f32_e32 v72, v50, v50
	v_mul_f32_e32 v73, v51, v51
	v_cvt_pk_bf16_f32 v48, v60, v61
	v_cvt_pk_bf16_f32 v49, v62, v63
	v_cvt_pk_bf16_f32 v50, v56, v57
	v_cvt_pk_bf16_f32 v51, v58, v59
	v_mul_f32_e32 v52, v52, v52
	v_mul_f32_e32 v53, v53, v53
	v_mul_f32_e32 v54, v54, v54
	v_mul_f32_e32 v55, v55, v55
	global_store_dwordx4 v[66:67], v[48:51], off
	s_nop 1
	v_cvt_pk_bf16_f32 v48, v52, v53
	v_cvt_pk_bf16_f32 v49, v54, v55
	v_cvt_pk_bf16_f32 v50, v70, v71
	v_cvt_pk_bf16_f32 v51, v72, v73
	global_store_dwordx4 v[66:67], v[48:51], off offset:256
	s_waitcnt vmcnt(12)
	s_nop 1
	v_mov_b32_e32 v48, v222
	v_mov_b32_e32 v49, v223
	v_mov_b32_e32 v50, v224
	v_mov_b32_e32 v51, v225
	v_mov_b32_e32 v52, v49
	v_mov_b32_e32 v53, v50
	v_mov_b32_e32 v49, v51
	v_pk_add_f32 v[48:49], v[52:53], v[48:49]
	v_lshlrev_b64 v[50:51], 13, v[64:65]
	v_add_f32_e32 v48, v48, v49
	ds_bpermute_b32 v49, v159, v48
	v_lshl_add_u64 v[50:51], s[10:11], 0, v[50:51]
	v_lshl_add_u64 v[50:51], v[50:51], 0, v[146:147]
	s_waitcnt lgkmcnt(0)
	v_add_f32_e32 v52, v48, v49
	ds_bpermute_b32 v53, v160, v52
	v_add_u32_e32 v48, 0xa0, v148
	v_ashrrev_i32_e32 v49, 31, v48
	s_waitcnt lgkmcnt(0)
	v_add_f32_e32 v52, v52, v53
	v_fmamk_f32 v52, v52, 0x3a800000, v157
	v_mov_b32_e32 v54, v52
	v_lshlrev_b64 v[52:53], 6, v[48:49]
	v_lshl_add_u64 v[52:53], v[136:137], 0, v[52:53]
	v_rsq_f32_e32 v55, v54
	v_mul_f32_e32 v56, 0.5, v54
	v_mul_f32_e32 v54, v55, v55
	v_fma_f32 v56, -v56, v54, 0.5
	v_fma_f32 v54, v55, v56, v55
	v_pk_mul_f32 v[46:47], v[46:47], v[54:55] op_sel_hi:[1,0]
	v_pk_mul_f32 v[44:45], v[44:45], v[54:55] op_sel_hi:[1,0]
	v_pk_mul_f32 v[42:43], v[42:43], v[54:55] op_sel_hi:[1,0]
	v_pk_mul_f32 v[40:41], v[40:41], v[54:55] op_sel_hi:[1,0]
	v_pk_mul_f32 v[34:35], v[34:35], v[54:55] op_sel_hi:[1,0]
	v_pk_mul_f32 v[32:33], v[32:33], v[54:55] op_sel_hi:[1,0]
	v_pk_mul_f32 v[38:39], v[38:39], v[54:55] op_sel_hi:[1,0]
	v_pk_mul_f32 v[36:37], v[36:37], v[54:55] op_sel_hi:[1,0]
	v_max_f32_e32 v44, 0, v44
	v_max_f32_e32 v40, 0, v40
	v_max_f32_e32 v45, 0, v45
	v_max_f32_e32 v41, 0, v41
	v_max_f32_e32 v46, 0, v46
	v_max_f32_e32 v42, 0, v42
	v_max_f32_e32 v47, 0, v47
	v_max_f32_e32 v43, 0, v43
	v_max_f32_e32 v32, 0, v32
	v_max_f32_e32 v33, 0, v33
	v_max_f32_e32 v34, 0, v34
	v_max_f32_e32 v35, 0, v35
	v_max_f32_e32 v36, 0, v36
	v_max_f32_e32 v37, 0, v37
	v_max_f32_e32 v38, 0, v38
	v_max_f32_e32 v39, 0, v39
	v_mul_f32_e32 v44, v44, v44
	v_mul_f32_e32 v40, v40, v40
	v_mul_f32_e32 v45, v45, v45
	v_mul_f32_e32 v41, v41, v41
	v_mul_f32_e32 v46, v46, v46
	v_mul_f32_e32 v42, v42, v42
	v_mul_f32_e32 v47, v47, v47
	v_mul_f32_e32 v43, v43, v43
	v_mul_f32_e32 v54, v32, v32
	v_mul_f32_e32 v55, v33, v33
	v_mul_f32_e32 v56, v34, v34
	v_mul_f32_e32 v57, v35, v35
	v_cvt_pk_bf16_f32 v32, v44, v45
	v_cvt_pk_bf16_f32 v33, v46, v47
	v_cvt_pk_bf16_f32 v34, v40, v41
	v_cvt_pk_bf16_f32 v35, v42, v43
	v_mul_f32_e32 v36, v36, v36
	v_mul_f32_e32 v37, v37, v37
	v_mul_f32_e32 v38, v38, v38
	v_mul_f32_e32 v39, v39, v39
	global_store_dwordx4 v[50:51], v[32:35], off
	s_nop 1
	v_cvt_pk_bf16_f32 v32, v36, v37
	v_cvt_pk_bf16_f32 v33, v38, v39
	v_cvt_pk_bf16_f32 v34, v54, v55
	v_cvt_pk_bf16_f32 v35, v56, v57
	global_store_dwordx4 v[50:51], v[32:35], off offset:256
	s_waitcnt vmcnt(13)
	s_nop 1
	v_mov_b32_e32 v32, v226
	v_mov_b32_e32 v33, v227
	v_mov_b32_e32 v34, v228
	v_mov_b32_e32 v35, v229
	v_mov_b32_e32 v36, v33
	v_mov_b32_e32 v37, v34
	v_mov_b32_e32 v33, v35
	v_pk_add_f32 v[32:33], v[36:37], v[32:33]
	v_lshlrev_b64 v[34:35], 13, v[48:49]
	v_add_f32_e32 v32, v32, v33
	ds_bpermute_b32 v33, v159, v32
	v_lshl_add_u64 v[34:35], s[10:11], 0, v[34:35]
	v_lshl_add_u64 v[34:35], v[34:35], 0, v[146:147]
	s_waitcnt lgkmcnt(0)
	v_add_f32_e32 v36, v32, v33
	ds_bpermute_b32 v37, v160, v36
	v_add_u32_e32 v32, 0xb0, v148
	v_ashrrev_i32_e32 v33, 31, v32
	s_waitcnt lgkmcnt(0)
	v_add_f32_e32 v36, v36, v37
	v_fmamk_f32 v36, v36, 0x3a800000, v157
	v_mov_b32_e32 v38, v36
	v_lshlrev_b64 v[36:37], 6, v[32:33]
	v_lshl_add_u64 v[36:37], v[136:137], 0, v[36:37]
	v_rsq_f32_e32 v39, v38
	v_mul_f32_e32 v40, 0.5, v38
	v_mul_f32_e32 v38, v39, v39
	v_fma_f32 v40, -v40, v38, 0.5
	v_fma_f32 v38, v39, v40, v39
	v_pk_mul_f32 v[30:31], v[30:31], v[38:39] op_sel_hi:[1,0]
	v_pk_mul_f32 v[28:29], v[28:29], v[38:39] op_sel_hi:[1,0]
	v_pk_mul_f32 v[26:27], v[26:27], v[38:39] op_sel_hi:[1,0]
	v_pk_mul_f32 v[24:25], v[24:25], v[38:39] op_sel_hi:[1,0]
	v_pk_mul_f32 v[18:19], v[18:19], v[38:39] op_sel_hi:[1,0]
	v_pk_mul_f32 v[16:17], v[16:17], v[38:39] op_sel_hi:[1,0]
	v_pk_mul_f32 v[22:23], v[22:23], v[38:39] op_sel_hi:[1,0]
	v_pk_mul_f32 v[20:21], v[20:21], v[38:39] op_sel_hi:[1,0]
	v_max_f32_e32 v28, 0, v28
	v_max_f32_e32 v24, 0, v24
	v_max_f32_e32 v29, 0, v29
	v_max_f32_e32 v25, 0, v25
	v_max_f32_e32 v30, 0, v30
	v_max_f32_e32 v26, 0, v26
	v_max_f32_e32 v31, 0, v31
	v_max_f32_e32 v27, 0, v27
	v_max_f32_e32 v16, 0, v16
	v_max_f32_e32 v17, 0, v17
	v_max_f32_e32 v18, 0, v18
	v_max_f32_e32 v19, 0, v19
	v_max_f32_e32 v20, 0, v20
	v_max_f32_e32 v21, 0, v21
	v_max_f32_e32 v22, 0, v22
	v_max_f32_e32 v23, 0, v23
	v_mul_f32_e32 v28, v28, v28
	v_mul_f32_e32 v24, v24, v24
	v_mul_f32_e32 v29, v29, v29
	v_mul_f32_e32 v25, v25, v25
	v_mul_f32_e32 v30, v30, v30
	v_mul_f32_e32 v26, v26, v26
	v_mul_f32_e32 v31, v31, v31
	v_mul_f32_e32 v27, v27, v27
	v_mul_f32_e32 v38, v16, v16
	v_mul_f32_e32 v39, v17, v17
	v_mul_f32_e32 v40, v18, v18
	v_mul_f32_e32 v41, v19, v19
	v_cvt_pk_bf16_f32 v16, v28, v29
	v_cvt_pk_bf16_f32 v17, v30, v31
	v_cvt_pk_bf16_f32 v18, v24, v25
	v_cvt_pk_bf16_f32 v19, v26, v27
	v_mul_f32_e32 v20, v20, v20
	v_mul_f32_e32 v21, v21, v21
	v_mul_f32_e32 v22, v22, v22
	v_mul_f32_e32 v23, v23, v23
	global_store_dwordx4 v[34:35], v[16:19], off
	s_nop 1
	v_cvt_pk_bf16_f32 v16, v20, v21
	v_cvt_pk_bf16_f32 v17, v22, v23
	v_cvt_pk_bf16_f32 v18, v38, v39
	v_cvt_pk_bf16_f32 v19, v40, v41
	global_store_dwordx4 v[34:35], v[16:19], off offset:256
	s_waitcnt vmcnt(14)
	s_nop 1
	v_mov_b32_e32 v16, v230
	v_mov_b32_e32 v17, v231
	v_mov_b32_e32 v18, v232
	v_mov_b32_e32 v19, v233
	v_mov_b32_e32 v20, v17
	v_mov_b32_e32 v21, v18
	v_mov_b32_e32 v17, v19
	v_pk_add_f32 v[16:17], v[20:21], v[16:17]
	s_nop 0
	v_add_f32_e32 v16, v16, v17
	ds_bpermute_b32 v17, v159, v16
	s_waitcnt lgkmcnt(0)
	v_add_f32_e32 v16, v16, v17
	ds_bpermute_b32 v17, v160, v16
	s_waitcnt lgkmcnt(0)
	v_add_f32_e32 v16, v16, v17
	v_fmamk_f32 v16, v16, 0x3a800000, v157
	v_mov_b32_e32 v18, v16
	v_lshlrev_b64 v[16:17], 13, v[32:33]
	v_lshl_add_u64 v[16:17], s[10:11], 0, v[16:17]
	v_lshl_add_u64 v[16:17], v[16:17], 0, v[146:147]
	v_rsq_f32_e32 v19, v18
	v_mul_f32_e32 v20, 0.5, v18
	v_mul_f32_e32 v18, v19, v19
	v_fma_f32 v20, -v20, v18, 0.5
	v_fma_f32 v18, v19, v20, v19
	v_pk_mul_f32 v[14:15], v[14:15], v[18:19] op_sel_hi:[1,0]
	v_pk_mul_f32 v[12:13], v[12:13], v[18:19] op_sel_hi:[1,0]
	v_pk_mul_f32 v[10:11], v[10:11], v[18:19] op_sel_hi:[1,0]
	v_pk_mul_f32 v[8:9], v[8:9], v[18:19] op_sel_hi:[1,0]
	v_pk_mul_f32 v[2:3], v[2:3], v[18:19] op_sel_hi:[1,0]
	v_pk_mul_f32 v[0:1], v[0:1], v[18:19] op_sel_hi:[1,0]
	v_pk_mul_f32 v[6:7], v[6:7], v[18:19] op_sel_hi:[1,0]
	v_pk_mul_f32 v[4:5], v[4:5], v[18:19] op_sel_hi:[1,0]
	v_max_f32_e32 v12, 0, v12
	v_max_f32_e32 v8, 0, v8
	v_max_f32_e32 v13, 0, v13
	v_max_f32_e32 v9, 0, v9
	v_max_f32_e32 v14, 0, v14
	v_max_f32_e32 v10, 0, v10
	v_max_f32_e32 v15, 0, v15
	v_max_f32_e32 v11, 0, v11
	v_max_f32_e32 v0, 0, v0
	v_max_f32_e32 v1, 0, v1
	v_max_f32_e32 v2, 0, v2
	v_max_f32_e32 v3, 0, v3
	s_andn2_b64 vcc, exec, s[0:1]
	v_max_f32_e32 v4, 0, v4
	v_max_f32_e32 v5, 0, v5
	v_max_f32_e32 v6, 0, v6
	v_max_f32_e32 v7, 0, v7
	v_mul_f32_e32 v12, v12, v12
	v_mul_f32_e32 v8, v8, v8
	v_mul_f32_e32 v13, v13, v13
	v_mul_f32_e32 v9, v9, v9
	v_mul_f32_e32 v14, v14, v14
	v_mul_f32_e32 v10, v10, v10
	v_mul_f32_e32 v15, v15, v15
	v_mul_f32_e32 v11, v11, v11
	v_mul_f32_e32 v18, v0, v0
	v_mul_f32_e32 v19, v1, v1
	v_mul_f32_e32 v20, v2, v2
	v_mul_f32_e32 v21, v3, v3
	v_cvt_pk_bf16_f32 v0, v12, v13
	v_cvt_pk_bf16_f32 v1, v14, v15
	v_cvt_pk_bf16_f32 v2, v8, v9
	v_cvt_pk_bf16_f32 v3, v10, v11
	s_mov_b64 s[0:1], -1
	v_mul_f32_e32 v4, v4, v4
	v_mul_f32_e32 v5, v5, v5
	v_mul_f32_e32 v6, v6, v6
	v_mul_f32_e32 v7, v7, v7
	global_store_dwordx4 v[16:17], v[0:3], off
	s_nop 1
	v_cvt_pk_bf16_f32 v0, v4, v5
	v_cvt_pk_bf16_f32 v1, v6, v7
	v_cvt_pk_bf16_f32 v2, v18, v19
	v_cvt_pk_bf16_f32 v3, v20, v21
	global_store_dwordx4 v[16:17], v[0:3], off offset:256
	s_cbranch_vccnz .LBB0_1241
	s_andn2_b64 vcc, exec, s[8:9]
	s_cbranch_vccnz .LBB0_1240
	s_barrier
	s_branch .LBB0_1240
